# GEMM1 output Z (re-read by the mixer phase) stored with default cache policy instead of nontemporal
# speedup vs baseline: 1.0064x; 1.0064x over previous
; #define LAS __attribute__((address_space(3)))
; __device__ __forceinline__ unsigned cvt_pk_bf16(float lo, float hi) { unsigned r; asm volatile("v_cvt_pk_bf16_f32 %0, %1, %2" : "=v"(r) : "v"(lo), "v"(hi)); return r; }
; __device__ __forceinline__ float rinv_from(u64 v) { return rsqrtf((float)v * (1.0f / 16777216.0f) * (1.0f / 1024.0f) + RMS_EPS); }
;     __device__ __forceinline__ void operator()(const f32x4 (&acc)[2][2][4][2], const Unit& u, int wr, int wc, int fr, int fq) const {
;         const int ln = fr + 16 * fq; const int colw = u.pn * BM + 64 * wc;
;         if (colw >= nvalid) return;
;         float rl[2];
; #pragma unroll
;         for (int ai = 0; ai < 2; ++ai) rl[ai] = rinv_from(ssq[u.pm * BM + ai * HALF + wr * 64 + ln]);
;         LAS unsigned char* sl = stg + (wr * 4 + wc) * EPI_STG_SLICE;
;         const int rr = ln >> 3, cc = ln & 7;
; #pragma unroll
;         for (int ai = 0; ai < 2; ++ai)
; #pragma unroll
;             for (int m = 0; m < 4; ++m) {
;                 const float sc = __shfl(rl[ai], 16 * m + fr);
; #pragma unroll
;                 for (int bj = 0; bj < 2; ++bj) {
;                     f32x4 v0 = acc[ai][bj][m][0] * sc, v1 = acc[ai][bj][m][1] * sc;
;                     if (ACT == 1) {
; #pragma unroll
;                         for (int e = 0; e < 4; ++e) { float a = fmaxf(v0[e], 0.f), b = fmaxf(v1[e], 0.f); v0[e] = a * a; v1[e] = b * b; }
;                     }
;                     u32x4 w; w.x = cvt_pk_bf16(v0[0], v0[1]); w.y = cvt_pk_bf16(v0[2], v0[3]); w.z = cvt_pk_bf16(v1[0], v1[1]); w.w = cvt_pk_bf16(v1[2], v1[3]);
;                     *(LAS u32x4*)(sl + fr * 144 + bj * 64 + fq * 16) = w;
;                 }
;                 const int rowb = u.pm * BM + ai * HALF + wr * 64 + m * 16;
; #pragma unroll
;                 for (int i = 0; i < 2; ++i) { const int r = rr + 8 * i; const u32x4 q = *(const LAS u32x4*)(sl + r * 144 + cc * 16);
;                     __builtin_nontemporal_store(q, (u32x4*)(O + (size_t)(rowb + r) * ldc + colw + cc * 8)); }
.LBB0_114:
	s_lshl_b32 s3, s2, 8
	v_add_u32_e32 v162, s3, v155
	v_ashrrev_i32_e32 v163, 31, v162
	v_lshl_add_u64 v[162:163], v[162:163], 3, s[42:43]
	v_mov_b32_e32 v164, v156
	v_mov_b32_e32 v165, v157
	s_nop 0
	v_mov_b32_e32 v162, v159
	s_mov_b32 s2, 0x33800000
	s_ashr_i32 s27, s26, 31
	s_add_i32 s6, s3, s81
	v_mov_b32_e32 v163, v160
	v_ffbh_u32_e32 v153, v165
	v_min_u32_e32 v153, 32, v153
	v_lshlrev_b64 v[164:165], v153, v[164:165]
	v_min_u32_e32 v161, 1, v164
	v_or_b32_e32 v161, v165, v161
	v_cvt_f32_u32_e32 v161, v161
	v_sub_u32_e32 v153, 32, v153
	v_ldexp_f32 v165, v161, v153
	v_ffbh_u32_e32 v153, v163
	v_min_u32_e32 v153, 32, v153
	v_lshlrev_b64 v[162:163], v153, v[162:163]
	v_min_u32_e32 v161, 1, v162
	v_or_b32_e32 v161, v163, v161
	v_cvt_f32_u32_e32 v161, v161
	v_sub_u32_e32 v153, 32, v153
	v_ldexp_f32 v164, v161, v153
	v_pk_mul_f32 v[162:163], v[164:165], s[2:3] op_sel_hi:[1,0]
	s_mov_b32 s2, 0x3a800000
	v_pk_fma_f32 v[162:163], v[162:163], s[2:3], v[138:139] op_sel_hi:[1,0,0]
	s_add_i32 s2, s3, s77
	v_mul_f32_e32 v153, 0x4b800000, v163
	v_cmp_gt_f32_e64 s[38:39], s70, v163
	v_cmp_gt_f32_e32 vcc, s70, v162
	s_nop 0
	v_cndmask_b32_e64 v153, v163, v153, s[38:39]
	v_rsq_f32_e32 v153, v153
	s_nop 0
	v_mul_f32_e32 v161, 0x45800000, v153
	v_cndmask_b32_e64 v163, v153, v161, s[38:39]
	v_mul_f32_e32 v153, 0x4b800000, v162
	v_cndmask_b32_e32 v153, v162, v153, vcc
	v_rsq_f32_e32 v153, v153
	s_lshl_b64 s[38:39], s[26:27], 1
	v_mul_f32_e32 v161, 0x45800000, v153
	v_cndmask_b32_e32 v161, v153, v161, vcc
	v_and_or_b32 v153, v177, 64, v1
	v_lshlrev_b32_e32 v162, 2, v153
	ds_bpermute_b32 v192, v162, v163
	ds_bpermute_b32 v194, v162, v163 offset:64
	ds_bpermute_b32 v196, v162, v163 offset:128
	ds_bpermute_b32 v198, v162, v163 offset:192
	ds_bpermute_b32 v200, v162, v161
	ds_bpermute_b32 v202, v162, v161 offset:64
	ds_bpermute_b32 v204, v162, v161 offset:128
	ds_bpermute_b32 v206, v162, v161 offset:192
	v_and_b32_e32 v210, 1, v177
	v_and_b32_e32 v211, 14, v177
	v_cmp_eq_u32_e64 s[92:93], 0, v210
	v_cmp_ne_u32_e64 s[98:99], 0, v210
	v_mul_u32_u24_e32 v208, 0x1300, v211
	s_mul_i32 s7, s2, 0x1300
	v_lshl_add_u32 v208, v210, 6, v208
	v_bfe_u32 v211, v177, 4, 2
	v_lshl_add_u32 v208, v211, 4, v208
	v_add_u32_e32 v209, 0x1300, v208
	s_add_u32 s62, s40, s7
	s_addc_u32 s63, s41, 0
	s_lshl_b32 s7, s26, 1
	s_add_u32 s62, s62, s7
	s_addc_u32 s63, s63, 0
	s_waitcnt lgkmcnt(7)
	s_mov_b32 s64, s62
	s_mov_b32 s65, s63
	v_pk_mul_f32 v[126:127], v[126:127], v[192:193] op_sel_hi:[1,0]
	v_pk_mul_f32 v[128:129], v[128:129], v[192:193] op_sel_hi:[1,0]
	v_pk_mul_f32 v[122:123], v[122:123], v[192:193] op_sel_hi:[1,0]
	v_pk_mul_f32 v[124:125], v[124:125], v[192:193] op_sel_hi:[1,0]
	v_cvt_pk_bf16_f32 v126, v126, v127
	v_cvt_pk_bf16_f32 v127, v128, v129
	v_cvt_pk_bf16_f32 v128, v122, v123
	v_cvt_pk_bf16_f32 v129, v124, v125
	v_pk_mul_f32 v[118:119], v[118:119], v[192:193] op_sel_hi:[1,0]
	v_pk_mul_f32 v[120:121], v[120:121], v[192:193] op_sel_hi:[1,0]
	v_pk_mul_f32 v[114:115], v[114:115], v[192:193] op_sel_hi:[1,0]
	v_pk_mul_f32 v[116:117], v[116:117], v[192:193] op_sel_hi:[1,0]
	v_cvt_pk_bf16_f32 v118, v118, v119
	v_cvt_pk_bf16_f32 v119, v120, v121
	v_cvt_pk_bf16_f32 v120, v114, v115
	v_cvt_pk_bf16_f32 v121, v116, v117
	s_mov_b64 vcc, s[98:99]
	v_cndmask_b32_dpp v122, v126, v118, vcc quad_perm:[1,0,3,2] row_mask:0xf bank_mask:0xf
	v_cndmask_b32_dpp v123, v127, v119, vcc quad_perm:[1,0,3,2] row_mask:0xf bank_mask:0xf
	v_cndmask_b32_dpp v124, v128, v120, vcc quad_perm:[1,0,3,2] row_mask:0xf bank_mask:0xf
	v_cndmask_b32_dpp v125, v129, v121, vcc quad_perm:[1,0,3,2] row_mask:0xf bank_mask:0xf
	s_mov_b64 vcc, s[92:93]
	v_cndmask_b32_dpp v126, v118, v126, vcc quad_perm:[1,0,3,2] row_mask:0xf bank_mask:0xf
	v_cndmask_b32_dpp v127, v119, v127, vcc quad_perm:[1,0,3,2] row_mask:0xf bank_mask:0xf
	v_cndmask_b32_dpp v128, v120, v128, vcc quad_perm:[1,0,3,2] row_mask:0xf bank_mask:0xf
	v_cndmask_b32_dpp v129, v121, v129, vcc quad_perm:[1,0,3,2] row_mask:0xf bank_mask:0xf
	global_store_dwordx4 v208, v[126:129], s[64:65]
	global_store_dwordx4 v209, v[122:125], s[64:65]
	s_waitcnt lgkmcnt(6)
	s_add_u32 s64, s62, 0x13000
	s_addc_u32 s65, s63, 0
	v_pk_mul_f32 v[110:111], v[110:111], v[194:195] op_sel_hi:[1,0]
	v_pk_mul_f32 v[112:113], v[112:113], v[194:195] op_sel_hi:[1,0]
	v_pk_mul_f32 v[106:107], v[106:107], v[194:195] op_sel_hi:[1,0]
	v_pk_mul_f32 v[108:109], v[108:109], v[194:195] op_sel_hi:[1,0]
	v_cvt_pk_bf16_f32 v110, v110, v111
	v_cvt_pk_bf16_f32 v111, v112, v113
	v_cvt_pk_bf16_f32 v112, v106, v107
	v_cvt_pk_bf16_f32 v113, v108, v109
	v_pk_mul_f32 v[102:103], v[102:103], v[194:195] op_sel_hi:[1,0]
	v_pk_mul_f32 v[104:105], v[104:105], v[194:195] op_sel_hi:[1,0]
	v_pk_mul_f32 v[98:99], v[98:99], v[194:195] op_sel_hi:[1,0]
	v_pk_mul_f32 v[100:101], v[100:101], v[194:195] op_sel_hi:[1,0]
	v_cvt_pk_bf16_f32 v102, v102, v103
	v_cvt_pk_bf16_f32 v103, v104, v105
	v_cvt_pk_bf16_f32 v104, v98, v99
	v_cvt_pk_bf16_f32 v105, v100, v101
	s_mov_b64 vcc, s[98:99]
	v_cndmask_b32_dpp v106, v110, v102, vcc quad_perm:[1,0,3,2] row_mask:0xf bank_mask:0xf
	v_cndmask_b32_dpp v107, v111, v103, vcc quad_perm:[1,0,3,2] row_mask:0xf bank_mask:0xf
	v_cndmask_b32_dpp v108, v112, v104, vcc quad_perm:[1,0,3,2] row_mask:0xf bank_mask:0xf
	v_cndmask_b32_dpp v109, v113, v105, vcc quad_perm:[1,0,3,2] row_mask:0xf bank_mask:0xf
	s_mov_b64 vcc, s[92:93]
	v_cndmask_b32_dpp v110, v102, v110, vcc quad_perm:[1,0,3,2] row_mask:0xf bank_mask:0xf
	v_cndmask_b32_dpp v111, v103, v111, vcc quad_perm:[1,0,3,2] row_mask:0xf bank_mask:0xf
	v_cndmask_b32_dpp v112, v104, v112, vcc quad_perm:[1,0,3,2] row_mask:0xf bank_mask:0xf
	v_cndmask_b32_dpp v113, v105, v113, vcc quad_perm:[1,0,3,2] row_mask:0xf bank_mask:0xf
	global_store_dwordx4 v208, v[110:113], s[64:65]
	global_store_dwordx4 v209, v[106:109], s[64:65]
	s_waitcnt lgkmcnt(5)
; #define LAS __attribute__((address_space(3)))
; __device__ __forceinline__ unsigned cvt_pk_bf16(float lo, float hi) { unsigned r; asm volatile("v_cvt_pk_bf16_f32 %0, %1, %2" : "=v"(r) : "v"(lo), "v"(hi)); return r; }
;     __device__ __forceinline__ void operator()(const f32x4 (&acc)[2][2][4][2], const Unit& u, int wr, int wc, int fr, int fq) const {
;     ...
;         for (int ai = 0; ai < 2; ++ai)
; #pragma unroll
;             for (int m = 0; m < 4; ++m) {
;                 const float sc = __shfl(rl[ai], 16 * m + fr);
; #pragma unroll
;                 for (int bj = 0; bj < 2; ++bj) {
;                     f32x4 v0 = acc[ai][bj][m][0] * sc, v1 = acc[ai][bj][m][1] * sc;
;                     if (ACT == 1) {
; #pragma unroll
;                         for (int e = 0; e < 4; ++e) { float a = fmaxf(v0[e], 0.f), b = fmaxf(v1[e], 0.f); v0[e] = a * a; v1[e] = b * b; }
;                     }
;                     u32x4 w; w.x = cvt_pk_bf16(v0[0], v0[1]); w.y = cvt_pk_bf16(v0[2], v0[3]); w.z = cvt_pk_bf16(v1[0], v1[1]); w.w = cvt_pk_bf16(v1[2], v1[3]);
;                     *(LAS u32x4*)(sl + fr * 144 + bj * 64 + fq * 16) = w;
;                 }
;                 const int rowb = u.pm * BM + ai * HALF + wr * 64 + m * 16;
; #pragma unroll
;                 for (int i = 0; i < 2; ++i) { const int r = rr + 8 * i; const u32x4 q = *(const LAS u32x4*)(sl + r * 144 + cc * 16);
;                     __builtin_nontemporal_store(q, (u32x4*)(O + (size_t)(rowb + r) * ldc + colw + cc * 8)); }
	s_add_u32 s64, s62, 0x26000
	s_addc_u32 s65, s63, 0
	v_pk_mul_f32 v[94:95], v[94:95], v[196:197] op_sel_hi:[1,0]
	v_pk_mul_f32 v[96:97], v[96:97], v[196:197] op_sel_hi:[1,0]
	v_pk_mul_f32 v[90:91], v[90:91], v[196:197] op_sel_hi:[1,0]
	v_pk_mul_f32 v[92:93], v[92:93], v[196:197] op_sel_hi:[1,0]
	v_cvt_pk_bf16_f32 v94, v94, v95
	v_cvt_pk_bf16_f32 v95, v96, v97
	v_cvt_pk_bf16_f32 v96, v90, v91
	v_cvt_pk_bf16_f32 v97, v92, v93
	v_pk_mul_f32 v[86:87], v[86:87], v[196:197] op_sel_hi:[1,0]
	v_pk_mul_f32 v[88:89], v[88:89], v[196:197] op_sel_hi:[1,0]
	v_pk_mul_f32 v[82:83], v[82:83], v[196:197] op_sel_hi:[1,0]
	v_pk_mul_f32 v[84:85], v[84:85], v[196:197] op_sel_hi:[1,0]
	v_cvt_pk_bf16_f32 v86, v86, v87
	v_cvt_pk_bf16_f32 v87, v88, v89
	v_cvt_pk_bf16_f32 v88, v82, v83
	v_cvt_pk_bf16_f32 v89, v84, v85
	s_mov_b64 vcc, s[98:99]
	v_cndmask_b32_dpp v90, v94, v86, vcc quad_perm:[1,0,3,2] row_mask:0xf bank_mask:0xf
	v_cndmask_b32_dpp v91, v95, v87, vcc quad_perm:[1,0,3,2] row_mask:0xf bank_mask:0xf
	v_cndmask_b32_dpp v92, v96, v88, vcc quad_perm:[1,0,3,2] row_mask:0xf bank_mask:0xf
	v_cndmask_b32_dpp v93, v97, v89, vcc quad_perm:[1,0,3,2] row_mask:0xf bank_mask:0xf
	s_mov_b64 vcc, s[92:93]
	v_cndmask_b32_dpp v94, v86, v94, vcc quad_perm:[1,0,3,2] row_mask:0xf bank_mask:0xf
	v_cndmask_b32_dpp v95, v87, v95, vcc quad_perm:[1,0,3,2] row_mask:0xf bank_mask:0xf
	v_cndmask_b32_dpp v96, v88, v96, vcc quad_perm:[1,0,3,2] row_mask:0xf bank_mask:0xf
	v_cndmask_b32_dpp v97, v89, v97, vcc quad_perm:[1,0,3,2] row_mask:0xf bank_mask:0xf
	global_store_dwordx4 v208, v[94:97], s[64:65]
	global_store_dwordx4 v209, v[90:93], s[64:65]
	s_waitcnt lgkmcnt(4)
	s_add_u32 s64, s62, 0x39000
	s_addc_u32 s65, s63, 0
	v_pk_mul_f32 v[78:79], v[78:79], v[198:199] op_sel_hi:[1,0]
	v_pk_mul_f32 v[80:81], v[80:81], v[198:199] op_sel_hi:[1,0]
	v_pk_mul_f32 v[74:75], v[74:75], v[198:199] op_sel_hi:[1,0]
	v_pk_mul_f32 v[76:77], v[76:77], v[198:199] op_sel_hi:[1,0]
	v_cvt_pk_bf16_f32 v78, v78, v79
	v_cvt_pk_bf16_f32 v79, v80, v81
	v_cvt_pk_bf16_f32 v80, v74, v75
	v_cvt_pk_bf16_f32 v81, v76, v77
	v_pk_mul_f32 v[70:71], v[70:71], v[198:199] op_sel_hi:[1,0]
	v_pk_mul_f32 v[72:73], v[72:73], v[198:199] op_sel_hi:[1,0]
	v_pk_mul_f32 v[66:67], v[66:67], v[198:199] op_sel_hi:[1,0]
	v_pk_mul_f32 v[68:69], v[68:69], v[198:199] op_sel_hi:[1,0]
	v_cvt_pk_bf16_f32 v70, v70, v71
	v_cvt_pk_bf16_f32 v71, v72, v73
	v_cvt_pk_bf16_f32 v72, v66, v67
	v_cvt_pk_bf16_f32 v73, v68, v69
	s_mov_b64 vcc, s[98:99]
	v_cndmask_b32_dpp v74, v78, v70, vcc quad_perm:[1,0,3,2] row_mask:0xf bank_mask:0xf
	v_cndmask_b32_dpp v75, v79, v71, vcc quad_perm:[1,0,3,2] row_mask:0xf bank_mask:0xf
	v_cndmask_b32_dpp v76, v80, v72, vcc quad_perm:[1,0,3,2] row_mask:0xf bank_mask:0xf
	v_cndmask_b32_dpp v77, v81, v73, vcc quad_perm:[1,0,3,2] row_mask:0xf bank_mask:0xf
	s_mov_b64 vcc, s[92:93]
	v_cndmask_b32_dpp v78, v70, v78, vcc quad_perm:[1,0,3,2] row_mask:0xf bank_mask:0xf
	v_cndmask_b32_dpp v79, v71, v79, vcc quad_perm:[1,0,3,2] row_mask:0xf bank_mask:0xf
	v_cndmask_b32_dpp v80, v72, v80, vcc quad_perm:[1,0,3,2] row_mask:0xf bank_mask:0xf
	v_cndmask_b32_dpp v81, v73, v81, vcc quad_perm:[1,0,3,2] row_mask:0xf bank_mask:0xf
	global_store_dwordx4 v208, v[78:81], s[64:65]
	global_store_dwordx4 v209, v[74:77], s[64:65]
	s_waitcnt lgkmcnt(3)
	s_add_u32 s64, s62, 0x98000
	s_addc_u32 s65, s63, 0
	v_pk_mul_f32 v[62:63], v[62:63], v[200:201] op_sel_hi:[1,0]
	v_pk_mul_f32 v[64:65], v[64:65], v[200:201] op_sel_hi:[1,0]
	v_pk_mul_f32 v[58:59], v[58:59], v[200:201] op_sel_hi:[1,0]
	v_pk_mul_f32 v[60:61], v[60:61], v[200:201] op_sel_hi:[1,0]
	v_cvt_pk_bf16_f32 v62, v62, v63
	v_cvt_pk_bf16_f32 v63, v64, v65
	v_cvt_pk_bf16_f32 v64, v58, v59
	v_cvt_pk_bf16_f32 v65, v60, v61
	v_pk_mul_f32 v[54:55], v[54:55], v[200:201] op_sel_hi:[1,0]
	v_pk_mul_f32 v[56:57], v[56:57], v[200:201] op_sel_hi:[1,0]
	v_pk_mul_f32 v[50:51], v[50:51], v[200:201] op_sel_hi:[1,0]
	v_pk_mul_f32 v[52:53], v[52:53], v[200:201] op_sel_hi:[1,0]
	v_cvt_pk_bf16_f32 v54, v54, v55
	v_cvt_pk_bf16_f32 v55, v56, v57
	v_cvt_pk_bf16_f32 v56, v50, v51
	v_cvt_pk_bf16_f32 v57, v52, v53
	s_mov_b64 vcc, s[98:99]
	v_cndmask_b32_dpp v58, v62, v54, vcc quad_perm:[1,0,3,2] row_mask:0xf bank_mask:0xf
	v_cndmask_b32_dpp v59, v63, v55, vcc quad_perm:[1,0,3,2] row_mask:0xf bank_mask:0xf
	v_cndmask_b32_dpp v60, v64, v56, vcc quad_perm:[1,0,3,2] row_mask:0xf bank_mask:0xf
	v_cndmask_b32_dpp v61, v65, v57, vcc quad_perm:[1,0,3,2] row_mask:0xf bank_mask:0xf
	s_mov_b64 vcc, s[92:93]
	v_cndmask_b32_dpp v62, v54, v62, vcc quad_perm:[1,0,3,2] row_mask:0xf bank_mask:0xf
	v_cndmask_b32_dpp v63, v55, v63, vcc quad_perm:[1,0,3,2] row_mask:0xf bank_mask:0xf
	v_cndmask_b32_dpp v64, v56, v64, vcc quad_perm:[1,0,3,2] row_mask:0xf bank_mask:0xf
	v_cndmask_b32_dpp v65, v57, v65, vcc quad_perm:[1,0,3,2] row_mask:0xf bank_mask:0xf
	global_store_dwordx4 v208, v[62:65], s[64:65]
	global_store_dwordx4 v209, v[58:61], s[64:65]
	s_waitcnt lgkmcnt(2)
; #define LAS __attribute__((address_space(3)))
; __device__ __forceinline__ unsigned cvt_pk_bf16(float lo, float hi) { unsigned r; asm volatile("v_cvt_pk_bf16_f32 %0, %1, %2" : "=v"(r) : "v"(lo), "v"(hi)); return r; }
;     __device__ __forceinline__ void operator()(const f32x4 (&acc)[2][2][4][2], const Unit& u, int wr, int wc, int fr, int fq) const {
;     ...
;         for (int ai = 0; ai < 2; ++ai)
; #pragma unroll
;             for (int m = 0; m < 4; ++m) {
;                 const float sc = __shfl(rl[ai], 16 * m + fr);
; #pragma unroll
;                 for (int bj = 0; bj < 2; ++bj) {
;                     f32x4 v0 = acc[ai][bj][m][0] * sc, v1 = acc[ai][bj][m][1] * sc;
;                     if (ACT == 1) {
; #pragma unroll
;                         for (int e = 0; e < 4; ++e) { float a = fmaxf(v0[e], 0.f), b = fmaxf(v1[e], 0.f); v0[e] = a * a; v1[e] = b * b; }
;                     }
;                     u32x4 w; w.x = cvt_pk_bf16(v0[0], v0[1]); w.y = cvt_pk_bf16(v0[2], v0[3]); w.z = cvt_pk_bf16(v1[0], v1[1]); w.w = cvt_pk_bf16(v1[2], v1[3]);
;                     *(LAS u32x4*)(sl + fr * 144 + bj * 64 + fq * 16) = w;
;                 }
;                 const int rowb = u.pm * BM + ai * HALF + wr * 64 + m * 16;
; #pragma unroll
;                 for (int i = 0; i < 2; ++i) { const int r = rr + 8 * i; const u32x4 q = *(const LAS u32x4*)(sl + r * 144 + cc * 16);
;                     __builtin_nontemporal_store(q, (u32x4*)(O + (size_t)(rowb + r) * ldc + colw + cc * 8)); }
	s_add_u32 s64, s62, 0xab000
	s_addc_u32 s65, s63, 0
	v_pk_mul_f32 v[46:47], v[46:47], v[202:203] op_sel_hi:[1,0]
	v_pk_mul_f32 v[48:49], v[48:49], v[202:203] op_sel_hi:[1,0]
	v_pk_mul_f32 v[42:43], v[42:43], v[202:203] op_sel_hi:[1,0]
	v_pk_mul_f32 v[44:45], v[44:45], v[202:203] op_sel_hi:[1,0]
	v_cvt_pk_bf16_f32 v46, v46, v47
	v_cvt_pk_bf16_f32 v47, v48, v49
	v_cvt_pk_bf16_f32 v48, v42, v43
	v_cvt_pk_bf16_f32 v49, v44, v45
	v_pk_mul_f32 v[38:39], v[38:39], v[202:203] op_sel_hi:[1,0]
	v_pk_mul_f32 v[40:41], v[40:41], v[202:203] op_sel_hi:[1,0]
	v_pk_mul_f32 v[34:35], v[34:35], v[202:203] op_sel_hi:[1,0]
	v_pk_mul_f32 v[36:37], v[36:37], v[202:203] op_sel_hi:[1,0]
	v_cvt_pk_bf16_f32 v38, v38, v39
	v_cvt_pk_bf16_f32 v39, v40, v41
	v_cvt_pk_bf16_f32 v40, v34, v35
	v_cvt_pk_bf16_f32 v41, v36, v37
	s_mov_b64 vcc, s[98:99]
	v_cndmask_b32_dpp v42, v46, v38, vcc quad_perm:[1,0,3,2] row_mask:0xf bank_mask:0xf
	v_cndmask_b32_dpp v43, v47, v39, vcc quad_perm:[1,0,3,2] row_mask:0xf bank_mask:0xf
	v_cndmask_b32_dpp v44, v48, v40, vcc quad_perm:[1,0,3,2] row_mask:0xf bank_mask:0xf
	v_cndmask_b32_dpp v45, v49, v41, vcc quad_perm:[1,0,3,2] row_mask:0xf bank_mask:0xf
	s_mov_b64 vcc, s[92:93]
	v_cndmask_b32_dpp v46, v38, v46, vcc quad_perm:[1,0,3,2] row_mask:0xf bank_mask:0xf
	v_cndmask_b32_dpp v47, v39, v47, vcc quad_perm:[1,0,3,2] row_mask:0xf bank_mask:0xf
	v_cndmask_b32_dpp v48, v40, v48, vcc quad_perm:[1,0,3,2] row_mask:0xf bank_mask:0xf
	v_cndmask_b32_dpp v49, v41, v49, vcc quad_perm:[1,0,3,2] row_mask:0xf bank_mask:0xf
	global_store_dwordx4 v208, v[46:49], s[64:65]
	global_store_dwordx4 v209, v[42:45], s[64:65]
	s_waitcnt lgkmcnt(1)
	s_add_u32 s64, s62, 0xbe000
	s_addc_u32 s65, s63, 0
	v_pk_mul_f32 v[30:31], v[30:31], v[204:205] op_sel_hi:[1,0]
	v_pk_mul_f32 v[32:33], v[32:33], v[204:205] op_sel_hi:[1,0]
	v_pk_mul_f32 v[26:27], v[26:27], v[204:205] op_sel_hi:[1,0]
	v_pk_mul_f32 v[28:29], v[28:29], v[204:205] op_sel_hi:[1,0]
	v_cvt_pk_bf16_f32 v30, v30, v31
	v_cvt_pk_bf16_f32 v31, v32, v33
	v_cvt_pk_bf16_f32 v32, v26, v27
	v_cvt_pk_bf16_f32 v33, v28, v29
	v_pk_mul_f32 v[22:23], v[22:23], v[204:205] op_sel_hi:[1,0]
	v_pk_mul_f32 v[24:25], v[24:25], v[204:205] op_sel_hi:[1,0]
	v_pk_mul_f32 v[18:19], v[18:19], v[204:205] op_sel_hi:[1,0]
	v_pk_mul_f32 v[20:21], v[20:21], v[204:205] op_sel_hi:[1,0]
	v_cvt_pk_bf16_f32 v22, v22, v23
	v_cvt_pk_bf16_f32 v23, v24, v25
	v_cvt_pk_bf16_f32 v24, v18, v19
	v_cvt_pk_bf16_f32 v25, v20, v21
	s_mov_b64 vcc, s[98:99]
	v_cndmask_b32_dpp v26, v30, v22, vcc quad_perm:[1,0,3,2] row_mask:0xf bank_mask:0xf
	v_cndmask_b32_dpp v27, v31, v23, vcc quad_perm:[1,0,3,2] row_mask:0xf bank_mask:0xf
	v_cndmask_b32_dpp v28, v32, v24, vcc quad_perm:[1,0,3,2] row_mask:0xf bank_mask:0xf
	v_cndmask_b32_dpp v29, v33, v25, vcc quad_perm:[1,0,3,2] row_mask:0xf bank_mask:0xf
	s_mov_b64 vcc, s[92:93]
	v_cndmask_b32_dpp v30, v22, v30, vcc quad_perm:[1,0,3,2] row_mask:0xf bank_mask:0xf
	v_cndmask_b32_dpp v31, v23, v31, vcc quad_perm:[1,0,3,2] row_mask:0xf bank_mask:0xf
	v_cndmask_b32_dpp v32, v24, v32, vcc quad_perm:[1,0,3,2] row_mask:0xf bank_mask:0xf
	v_cndmask_b32_dpp v33, v25, v33, vcc quad_perm:[1,0,3,2] row_mask:0xf bank_mask:0xf
	global_store_dwordx4 v208, v[30:33], s[64:65]
	global_store_dwordx4 v209, v[26:29], s[64:65]
	s_waitcnt lgkmcnt(0)
	s_add_u32 s64, s62, 0xd1000
	s_addc_u32 s65, s63, 0
	v_pk_mul_f32 v[14:15], v[14:15], v[206:207] op_sel_hi:[1,0]
	v_pk_mul_f32 v[16:17], v[16:17], v[206:207] op_sel_hi:[1,0]
	v_pk_mul_f32 v[10:11], v[10:11], v[206:207] op_sel_hi:[1,0]
	v_pk_mul_f32 v[12:13], v[12:13], v[206:207] op_sel_hi:[1,0]
	v_cvt_pk_bf16_f32 v14, v14, v15
	v_cvt_pk_bf16_f32 v15, v16, v17
	v_cvt_pk_bf16_f32 v16, v10, v11
	v_cvt_pk_bf16_f32 v17, v12, v13
	v_pk_mul_f32 v[6:7], v[6:7], v[206:207] op_sel_hi:[1,0]
	v_pk_mul_f32 v[8:9], v[8:9], v[206:207] op_sel_hi:[1,0]
	v_pk_mul_f32 v[2:3], v[2:3], v[206:207] op_sel_hi:[1,0]
	v_pk_mul_f32 v[4:5], v[4:5], v[206:207] op_sel_hi:[1,0]
	v_cvt_pk_bf16_f32 v6, v6, v7
	v_cvt_pk_bf16_f32 v7, v8, v9
	v_cvt_pk_bf16_f32 v8, v2, v3
	v_cvt_pk_bf16_f32 v9, v4, v5
	s_mov_b64 vcc, s[98:99]
	v_cndmask_b32_dpp v10, v14, v6, vcc quad_perm:[1,0,3,2] row_mask:0xf bank_mask:0xf
	v_cndmask_b32_dpp v11, v15, v7, vcc quad_perm:[1,0,3,2] row_mask:0xf bank_mask:0xf
	v_cndmask_b32_dpp v12, v16, v8, vcc quad_perm:[1,0,3,2] row_mask:0xf bank_mask:0xf
	v_cndmask_b32_dpp v13, v17, v9, vcc quad_perm:[1,0,3,2] row_mask:0xf bank_mask:0xf
	s_mov_b64 vcc, s[92:93]
	v_cndmask_b32_dpp v14, v6, v14, vcc quad_perm:[1,0,3,2] row_mask:0xf bank_mask:0xf
	v_cndmask_b32_dpp v15, v7, v15, vcc quad_perm:[1,0,3,2] row_mask:0xf bank_mask:0xf
	v_cndmask_b32_dpp v16, v8, v16, vcc quad_perm:[1,0,3,2] row_mask:0xf bank_mask:0xf
	v_cndmask_b32_dpp v17, v9, v17, vcc quad_perm:[1,0,3,2] row_mask:0xf bank_mask:0xf
	global_store_dwordx4 v208, v[14:17], s[64:65]
	global_store_dwordx4 v209, v[10:13], s[64:65]
	s_andn2_b64 vcc, exec, s[36:37]
	s_mov_b64 s[26:27], -1
	s_cbranch_vccnz .LBB0_105
